# SwiGLU epilogue: cross-lane row-sum reduction via v_permlane16/32_swap instead of ds_bpermute round trips (strategy 7)
# speedup vs baseline: 1.0064x; 1.0064x over previous
; __device__ __forceinline__ float rstd_from(const float* ps, int row, int off4, int n4, float inv_dim, int fq) {
;     float s = 0.f;
;     if (fq < n4) { const f32x4 v = *((const f32x4*)(ps + (size_t)row * 16) + off4 + fq); s = (v[0] + v[1]) + (v[2] + v[3]); }
;     s += __shfl_xor(s, 16); s += __shfl_xor(s, 32);
;     return rsqrtf(s * inv_dim + 1e-6f);
;     __device__ __forceinline__ void operator()(const f32x4 (&acc)[2][2][4][2], const Unit& u, int wr, int wc, int fr, int fq) const {
;     ...
;                 const int row = row0 + ai * HALF + m * 16;
;                 const float rs = rstd_from(ps, row, 0, 4, 1.f / 1024.f, fq);
.LBB0_1171:
	v_and_b32_e32 v143, 64, v204
	v_xor_b32_e32 v141, 16, v204
	v_add_u32_e32 v143, 64, v143
	v_cmp_lt_i32_e32 vcc, v141, v143
	v_lshl_add_u32 v140, s7, 8, v145
	v_lshl_or_b32 v142, s2, 7, v147
	v_cndmask_b32_e32 v141, v204, v141, vcc
	v_lshlrev_b32_e32 v149, 2, v141
	v_xor_b32_e32 v141, 32, v204
	v_cmp_lt_i32_e32 vcc, v141, v143
	v_ashrrev_i32_e32 v143, 31, v142
	s_movk_i32 s4, 0x2000
	v_cndmask_b32_e32 v141, v204, v141, vcc
	v_lshlrev_b32_e32 v150, 2, v141
	v_ashrrev_i32_e32 v141, 31, v140
	v_lshlrev_b64 v[152:153], 6, v[140:141]
	s_mov_b32 s5, 0
	v_lshl_add_u64 v[152:153], v[134:135], 0, v[152:153]
	v_lshl_add_u64 v[154:155], v[152:153], 0, s[4:5]
	global_load_dwordx4 v[156:159], v[152:153], off
	global_load_dwordx4 v[160:163], v[152:153], off offset:1024
	global_load_dwordx4 v[164:167], v[152:153], off offset:2048
	global_load_dwordx4 v[172:175], v[152:153], off offset:3072
	global_load_dwordx4 v[176:179], v[154:155], off
	global_load_dwordx4 v[180:183], v[154:155], off offset:1024
	global_load_dwordx4 v[184:187], v[154:155], off offset:2048
	global_load_dwordx4 v[188:191], v[154:155], off offset:3072
	v_mov_b64_e32 v[236:237], s[26:27]
	v_lshlrev_b64 v[238:239], 1, v[142:143]
	v_mad_i64_i32 v[234:235], s[4:5], v140, s17, v[236:237]
	s_lshl_b32 s4, s17, 4
	s_mov_b32 s5, 0
	v_lshl_add_u64 v[234:235], v[234:235], 0, v[238:239]
	v_lshl_add_u64 v[236:237], s[4:5], 0, v[234:235]
	v_lshl_add_u64 v[238:239], s[4:5], 1, v[234:235]
	v_lshl_add_u64 v[240:241], s[4:5], 1, v[236:237]
	s_waitcnt vmcnt(7)
	v_add_f32_e32 v156, v157, v156
	v_add_f32_e32 v158, v158, v159
	s_waitcnt vmcnt(6)
	v_add_f32_e32 v160, v161, v160
	v_add_f32_e32 v162, v162, v163
	s_waitcnt vmcnt(5)
	v_add_f32_e32 v164, v165, v164
	v_add_f32_e32 v166, v166, v167
	s_waitcnt vmcnt(4)
	v_add_f32_e32 v172, v173, v172
	v_add_f32_e32 v174, v174, v175
	s_waitcnt vmcnt(3)
	v_add_f32_e32 v176, v177, v176
	v_add_f32_e32 v178, v178, v179
	s_waitcnt vmcnt(2)
	v_add_f32_e32 v180, v181, v180
	v_add_f32_e32 v182, v182, v183
	s_waitcnt vmcnt(1)
	v_add_f32_e32 v184, v185, v184
	v_add_f32_e32 v186, v186, v187
	s_waitcnt vmcnt(0)
	v_add_f32_e32 v188, v189, v188
	v_add_f32_e32 v190, v190, v191
	v_add_f32_e32 v156, v156, v158
	v_add_f32_e32 v160, v160, v162
	v_add_f32_e32 v164, v164, v166
	v_add_f32_e32 v172, v172, v174
	v_add_f32_e32 v176, v176, v178
	v_add_f32_e32 v180, v180, v182
	v_add_f32_e32 v184, v184, v186
	v_add_f32_e32 v188, v188, v190
	v_mov_b32_e32 v157, v156
	v_mov_b32_e32 v161, v160
	v_mov_b32_e32 v165, v164
	v_mov_b32_e32 v173, v172
	v_mov_b32_e32 v177, v176
	v_mov_b32_e32 v181, v180
	v_mov_b32_e32 v185, v184
	v_mov_b32_e32 v189, v188
	v_permlane16_swap_b32_e32 v156, v157
	v_permlane16_swap_b32_e32 v160, v161
	v_permlane16_swap_b32_e32 v164, v165
	v_permlane16_swap_b32_e32 v172, v173
	v_permlane16_swap_b32_e32 v176, v177
	v_permlane16_swap_b32_e32 v180, v181
	v_permlane16_swap_b32_e32 v184, v185
	v_permlane16_swap_b32_e32 v188, v189
	v_add_f32_e32 v156, v156, v157
	v_add_f32_e32 v160, v160, v161
	v_add_f32_e32 v164, v164, v165
	v_add_f32_e32 v172, v172, v173
	v_add_f32_e32 v176, v176, v177
	v_add_f32_e32 v180, v180, v181
	v_add_f32_e32 v184, v184, v185
	v_add_f32_e32 v188, v188, v189
	v_mov_b32_e32 v157, v156
	v_mov_b32_e32 v161, v160
	v_mov_b32_e32 v165, v164
	v_mov_b32_e32 v173, v172
	v_mov_b32_e32 v177, v176
	v_mov_b32_e32 v181, v180
	v_mov_b32_e32 v185, v184
	v_mov_b32_e32 v189, v188
	v_permlane32_swap_b32_e32 v156, v157
	v_permlane32_swap_b32_e32 v160, v161
	v_permlane32_swap_b32_e32 v164, v165
	v_permlane32_swap_b32_e32 v172, v173
	v_permlane32_swap_b32_e32 v176, v177
	v_permlane32_swap_b32_e32 v180, v181
	v_permlane32_swap_b32_e32 v184, v185
	v_permlane32_swap_b32_e32 v188, v189
	v_add_f32_e32 v156, v156, v157
	v_add_f32_e32 v160, v160, v161
	v_add_f32_e32 v164, v164, v165
	v_add_f32_e32 v172, v172, v173
	v_add_f32_e32 v176, v176, v177
	v_add_f32_e32 v180, v180, v181
	v_add_f32_e32 v184, v184, v185
	v_add_f32_e32 v188, v188, v189
	v_fmamk_f32 v156, v156, 0x3a800000, v202
	v_fmamk_f32 v160, v160, 0x3a800000, v202
	v_fmamk_f32 v164, v164, 0x3a800000, v202
	v_fmamk_f32 v172, v172, 0x3a800000, v202
	v_fmamk_f32 v176, v176, 0x3a800000, v202
	v_fmamk_f32 v180, v180, 0x3a800000, v202
	v_fmamk_f32 v184, v184, 0x3a800000, v202
	v_fmamk_f32 v188, v188, 0x3a800000, v202
	v_cmp_gt_f32_e32 vcc, s33, v156
	v_cmp_gt_f32_e64 s[4:5], s33, v160
	v_mul_f32_e32 v157, 0x4b800000, v156
	v_mul_f32_e32 v161, 0x4b800000, v160
	v_cndmask_b32_e32 v156, v156, v157, vcc
	v_cndmask_b32_e64 v160, v160, v161, s[4:5]
	v_rsq_f32_e32 v156, v156
	v_rsq_f32_e32 v160, v160
	v_mul_f32_e32 v157, 0x45800000, v156
	v_mul_f32_e32 v161, 0x45800000, v160
	v_cndmask_b32_e32 v158, v156, v157, vcc
	v_cndmask_b32_e64 v162, v160, v161, s[4:5]
	v_cmp_gt_f32_e32 vcc, s33, v164
	v_cmp_gt_f32_e64 s[4:5], s33, v172
	v_mul_f32_e32 v165, 0x4b800000, v164
	v_mul_f32_e32 v173, 0x4b800000, v172
	v_cndmask_b32_e32 v164, v164, v165, vcc
	v_cndmask_b32_e64 v172, v172, v173, s[4:5]
	v_rsq_f32_e32 v164, v164
	v_rsq_f32_e32 v172, v172
	v_mul_f32_e32 v165, 0x45800000, v164
	v_mul_f32_e32 v173, 0x45800000, v172
	v_cndmask_b32_e32 v166, v164, v165, vcc
	v_cndmask_b32_e64 v174, v172, v173, s[4:5]
	v_cmp_gt_f32_e32 vcc, s33, v176
	v_cmp_gt_f32_e64 s[4:5], s33, v180
	v_mul_f32_e32 v177, 0x4b800000, v176
	v_mul_f32_e32 v181, 0x4b800000, v180
	v_cndmask_b32_e32 v176, v176, v177, vcc
	v_cndmask_b32_e64 v180, v180, v181, s[4:5]
	v_rsq_f32_e32 v176, v176
	v_rsq_f32_e32 v180, v180
	v_mul_f32_e32 v177, 0x45800000, v176
	v_mul_f32_e32 v181, 0x45800000, v180
	v_cndmask_b32_e32 v178, v176, v177, vcc
	v_cndmask_b32_e64 v182, v180, v181, s[4:5]
; __device__ __forceinline__ unsigned cvt_pk_bf16(float lo, float hi) { unsigned r; asm volatile("v_cvt_pk_bf16_f32 %0, %1, %2" : "=v"(r) : "v"(lo), "v"(hi)); return r; }
; __device__ __forceinline__ float rstd_from(const float* ps, int row, int off4, int n4, float inv_dim, int fq) {
;     ...
;     return rsqrtf(s * inv_dim + 1e-6f);
;     __device__ __forceinline__ void operator()(const f32x4 (&acc)[2][2][4][2], const Unit& u, int wr, int wc, int fr, int fq) const {
;     ...
;                     for (int e = 0; e < 4; ++e) { const float gt = acc[ai][0][m][n][e] * rs, up = acc[ai][1][m][n][e] * rs;
;                         hv[n * 4 + e] = gt * __builtin_amdgcn_rcpf(1.f + __builtin_amdgcn_exp2f(-1.4426950408889634f * gt)) * up; }
;                 u32x4 w; w.x = cvt_pk_bf16(hv[0], hv[1]); w.y = cvt_pk_bf16(hv[2], hv[3]); w.z = cvt_pk_bf16(hv[4], hv[5]); w.w = cvt_pk_bf16(hv[6], hv[7]);
;                 *(u32x4*)(H + (size_t)row * 2816 + col0) = w;
	v_cmp_gt_f32_e32 vcc, s33, v184
	v_cmp_gt_f32_e64 s[4:5], s33, v188
	v_mul_f32_e32 v185, 0x4b800000, v184
	v_mul_f32_e32 v189, 0x4b800000, v188
	v_cndmask_b32_e32 v184, v184, v185, vcc
	v_cndmask_b32_e64 v188, v188, v189, s[4:5]
	v_rsq_f32_e32 v184, v184
	v_rsq_f32_e32 v188, v188
	v_mul_f32_e32 v185, 0x45800000, v184
	v_mul_f32_e32 v189, 0x45800000, v188
	v_cndmask_b32_e32 v186, v184, v185, vcc
	v_cndmask_b32_e64 v190, v188, v189, s[4:5]
	s_lshl_b32 s4, s17, 4
	s_mov_b32 s5, 0
	v_mul_f32_e32 v120, v120, v158
	v_mul_f32_e32 v121, v121, v158
	v_mul_f32_e32 v122, v122, v158
	v_mul_f32_e32 v123, v123, v158
	v_mul_f32_e32 v112, v112, v158
	v_mul_f32_e32 v113, v113, v158
	v_mul_f32_e32 v114, v114, v158
	v_mul_f32_e32 v115, v115, v158
	v_mul_f32_e32 v218, 0xbfb8aa3b, v120
	v_mul_f32_e32 v219, 0xbfb8aa3b, v121
	v_mul_f32_e32 v220, 0xbfb8aa3b, v122
	v_mul_f32_e32 v221, 0xbfb8aa3b, v123
	v_mul_f32_e32 v222, 0xbfb8aa3b, v112
	v_mul_f32_e32 v223, 0xbfb8aa3b, v113
	v_mul_f32_e32 v224, 0xbfb8aa3b, v114
	v_mul_f32_e32 v225, 0xbfb8aa3b, v115
	v_exp_f32_e32 v218, v218
	v_exp_f32_e32 v219, v219
	v_exp_f32_e32 v220, v220
	v_exp_f32_e32 v221, v221
	v_exp_f32_e32 v222, v222
	v_exp_f32_e32 v223, v223
	v_exp_f32_e32 v224, v224
	v_exp_f32_e32 v225, v225
	v_add_f32_e32 v218, 1.0, v218
	v_add_f32_e32 v219, 1.0, v219
	v_add_f32_e32 v220, 1.0, v220
	v_add_f32_e32 v221, 1.0, v221
	v_add_f32_e32 v222, 1.0, v222
	v_add_f32_e32 v223, 1.0, v223
	v_add_f32_e32 v224, 1.0, v224
	v_add_f32_e32 v225, 1.0, v225
	v_rcp_f32_e32 v218, v218
	v_rcp_f32_e32 v219, v219
	v_rcp_f32_e32 v220, v220
	v_rcp_f32_e32 v221, v221
	v_rcp_f32_e32 v222, v222
	v_rcp_f32_e32 v223, v223
	v_rcp_f32_e32 v224, v224
	v_rcp_f32_e32 v225, v225
	v_mul_f32_e32 v218, v120, v218
	v_mul_f32_e32 v219, v121, v219
	v_mul_f32_e32 v220, v122, v220
	v_mul_f32_e32 v221, v123, v221
	v_mul_f32_e32 v222, v112, v222
	v_mul_f32_e32 v223, v113, v223
	v_mul_f32_e32 v224, v114, v224
	v_mul_f32_e32 v225, v115, v225
	v_mul_f32_e32 v124, v124, v158
	v_mul_f32_e32 v125, v125, v158
	v_mul_f32_e32 v126, v126, v158
	v_mul_f32_e32 v127, v127, v158
	v_mul_f32_e32 v116, v116, v158
	v_mul_f32_e32 v117, v117, v158
	v_mul_f32_e32 v118, v118, v158
	v_mul_f32_e32 v119, v119, v158
	v_mul_f32_e32 v124, v124, v218
	v_mul_f32_e32 v125, v125, v219
	v_mul_f32_e32 v126, v126, v220
	v_mul_f32_e32 v127, v127, v221
	v_mul_f32_e32 v116, v116, v222
	v_mul_f32_e32 v117, v117, v223
	v_mul_f32_e32 v118, v118, v224
	v_mul_f32_e32 v119, v119, v225
	v_cvt_pk_bf16_f32 v226, v124, v125
	v_cvt_pk_bf16_f32 v227, v126, v127
	v_cvt_pk_bf16_f32 v228, v116, v117
	v_cvt_pk_bf16_f32 v229, v118, v119
	global_store_dwordx4 v[234:235], v[226:229], off
	v_mul_f32_e32 v104, v104, v162
	v_mul_f32_e32 v105, v105, v162
	v_mul_f32_e32 v106, v106, v162
	v_mul_f32_e32 v107, v107, v162
	v_mul_f32_e32 v96, v96, v162
	v_mul_f32_e32 v97, v97, v162
	v_mul_f32_e32 v98, v98, v162
	v_mul_f32_e32 v99, v99, v162
	v_mul_f32_e32 v218, 0xbfb8aa3b, v104
	v_mul_f32_e32 v219, 0xbfb8aa3b, v105
	v_mul_f32_e32 v220, 0xbfb8aa3b, v106
	v_mul_f32_e32 v221, 0xbfb8aa3b, v107
	v_mul_f32_e32 v222, 0xbfb8aa3b, v96
	v_mul_f32_e32 v223, 0xbfb8aa3b, v97
	v_mul_f32_e32 v224, 0xbfb8aa3b, v98
	v_mul_f32_e32 v225, 0xbfb8aa3b, v99
	v_exp_f32_e32 v218, v218
	v_exp_f32_e32 v219, v219
	v_exp_f32_e32 v220, v220
	v_exp_f32_e32 v221, v221
	v_exp_f32_e32 v222, v222
	v_exp_f32_e32 v223, v223
	v_exp_f32_e32 v224, v224
	v_exp_f32_e32 v225, v225
	v_add_f32_e32 v218, 1.0, v218
	v_add_f32_e32 v219, 1.0, v219
	v_add_f32_e32 v220, 1.0, v220
	v_add_f32_e32 v221, 1.0, v221
	v_add_f32_e32 v222, 1.0, v222
	v_add_f32_e32 v223, 1.0, v223
	v_add_f32_e32 v224, 1.0, v224
	v_add_f32_e32 v225, 1.0, v225
	v_rcp_f32_e32 v218, v218
	v_rcp_f32_e32 v219, v219
	v_rcp_f32_e32 v220, v220
	v_rcp_f32_e32 v221, v221
	v_rcp_f32_e32 v222, v222
	v_rcp_f32_e32 v223, v223
	v_rcp_f32_e32 v224, v224
	v_rcp_f32_e32 v225, v225
	v_mul_f32_e32 v218, v104, v218
	v_mul_f32_e32 v219, v105, v219
	v_mul_f32_e32 v220, v106, v220
	v_mul_f32_e32 v221, v107, v221
	v_mul_f32_e32 v222, v96, v222
	v_mul_f32_e32 v223, v97, v223
	v_mul_f32_e32 v224, v98, v224
	v_mul_f32_e32 v225, v99, v225
	v_mul_f32_e32 v108, v108, v162
	v_mul_f32_e32 v109, v109, v162
	v_mul_f32_e32 v110, v110, v162
	v_mul_f32_e32 v111, v111, v162
	v_mul_f32_e32 v100, v100, v162
	v_mul_f32_e32 v101, v101, v162
	v_mul_f32_e32 v102, v102, v162
	v_mul_f32_e32 v103, v103, v162
	v_mul_f32_e32 v108, v108, v218
	v_mul_f32_e32 v109, v109, v219
	v_mul_f32_e32 v110, v110, v220
	v_mul_f32_e32 v111, v111, v221
	v_mul_f32_e32 v100, v100, v222
	v_mul_f32_e32 v101, v101, v223
	v_mul_f32_e32 v102, v102, v224
	v_mul_f32_e32 v103, v103, v225
	v_cvt_pk_bf16_f32 v230, v108, v109
	v_cvt_pk_bf16_f32 v231, v110, v111
	v_cvt_pk_bf16_f32 v232, v100, v101
	v_cvt_pk_bf16_f32 v233, v102, v103
	global_store_dwordx4 v[236:237], v[230:233], off
	v_mul_f32_e32 v88, v88, v166
	v_mul_f32_e32 v89, v89, v166
	v_mul_f32_e32 v90, v90, v166
	v_mul_f32_e32 v91, v91, v166
	v_mul_f32_e32 v80, v80, v166
	v_mul_f32_e32 v81, v81, v166
	v_mul_f32_e32 v82, v82, v166
	v_mul_f32_e32 v83, v83, v166
	v_mul_f32_e32 v218, 0xbfb8aa3b, v88
	v_mul_f32_e32 v219, 0xbfb8aa3b, v89
	v_mul_f32_e32 v220, 0xbfb8aa3b, v90
	v_mul_f32_e32 v221, 0xbfb8aa3b, v91
	v_mul_f32_e32 v222, 0xbfb8aa3b, v80
	v_mul_f32_e32 v223, 0xbfb8aa3b, v81
	v_mul_f32_e32 v224, 0xbfb8aa3b, v82
	v_mul_f32_e32 v225, 0xbfb8aa3b, v83
	v_exp_f32_e32 v218, v218
	v_exp_f32_e32 v219, v219
	v_exp_f32_e32 v220, v220
	v_exp_f32_e32 v221, v221
	v_exp_f32_e32 v222, v222
	v_exp_f32_e32 v223, v223
	v_exp_f32_e32 v224, v224
	v_exp_f32_e32 v225, v225
	v_add_f32_e32 v218, 1.0, v218
	v_add_f32_e32 v219, 1.0, v219
; __device__ __forceinline__ unsigned cvt_pk_bf16(float lo, float hi) { unsigned r; asm volatile("v_cvt_pk_bf16_f32 %0, %1, %2" : "=v"(r) : "v"(lo), "v"(hi)); return r; }
;     __device__ __forceinline__ void operator()(const f32x4 (&acc)[2][2][4][2], const Unit& u, int wr, int wc, int fr, int fq) const {
;     ...
;                     for (int e = 0; e < 4; ++e) { const float gt = acc[ai][0][m][n][e] * rs, up = acc[ai][1][m][n][e] * rs;
;                         hv[n * 4 + e] = gt * __builtin_amdgcn_rcpf(1.f + __builtin_amdgcn_exp2f(-1.4426950408889634f * gt)) * up; }
;                 u32x4 w; w.x = cvt_pk_bf16(hv[0], hv[1]); w.y = cvt_pk_bf16(hv[2], hv[3]); w.z = cvt_pk_bf16(hv[4], hv[5]); w.w = cvt_pk_bf16(hv[6], hv[7]);
;                 *(u32x4*)(H + (size_t)row * 2816 + col0) = w;
	v_add_f32_e32 v220, 1.0, v220
	v_add_f32_e32 v221, 1.0, v221
	v_add_f32_e32 v222, 1.0, v222
	v_add_f32_e32 v223, 1.0, v223
	v_add_f32_e32 v224, 1.0, v224
	v_add_f32_e32 v225, 1.0, v225
	v_rcp_f32_e32 v218, v218
	v_rcp_f32_e32 v219, v219
	v_rcp_f32_e32 v220, v220
	v_rcp_f32_e32 v221, v221
	v_rcp_f32_e32 v222, v222
	v_rcp_f32_e32 v223, v223
	v_rcp_f32_e32 v224, v224
	v_rcp_f32_e32 v225, v225
	v_mul_f32_e32 v218, v88, v218
	v_mul_f32_e32 v219, v89, v219
	v_mul_f32_e32 v220, v90, v220
	v_mul_f32_e32 v221, v91, v221
	v_mul_f32_e32 v222, v80, v222
	v_mul_f32_e32 v223, v81, v223
	v_mul_f32_e32 v224, v82, v224
	v_mul_f32_e32 v225, v83, v225
	v_mul_f32_e32 v92, v92, v166
	v_mul_f32_e32 v93, v93, v166
	v_mul_f32_e32 v94, v94, v166
	v_mul_f32_e32 v95, v95, v166
	v_mul_f32_e32 v84, v84, v166
	v_mul_f32_e32 v85, v85, v166
	v_mul_f32_e32 v86, v86, v166
	v_mul_f32_e32 v87, v87, v166
	v_mul_f32_e32 v92, v92, v218
	v_mul_f32_e32 v93, v93, v219
	v_mul_f32_e32 v94, v94, v220
	v_mul_f32_e32 v95, v95, v221
	v_mul_f32_e32 v84, v84, v222
	v_mul_f32_e32 v85, v85, v223
	v_mul_f32_e32 v86, v86, v224
	v_mul_f32_e32 v87, v87, v225
	v_cvt_pk_bf16_f32 v226, v92, v93
	v_cvt_pk_bf16_f32 v227, v94, v95
	v_cvt_pk_bf16_f32 v228, v84, v85
	v_cvt_pk_bf16_f32 v229, v86, v87
	global_store_dwordx4 v[238:239], v[226:229], off
	v_mul_f32_e32 v72, v72, v174
	v_mul_f32_e32 v73, v73, v174
	v_mul_f32_e32 v74, v74, v174
	v_mul_f32_e32 v75, v75, v174
	v_mul_f32_e32 v64, v64, v174
	v_mul_f32_e32 v65, v65, v174
	v_mul_f32_e32 v66, v66, v174
	v_mul_f32_e32 v67, v67, v174
	v_mul_f32_e32 v218, 0xbfb8aa3b, v72
	v_mul_f32_e32 v219, 0xbfb8aa3b, v73
	v_mul_f32_e32 v220, 0xbfb8aa3b, v74
	v_mul_f32_e32 v221, 0xbfb8aa3b, v75
	v_mul_f32_e32 v222, 0xbfb8aa3b, v64
	v_mul_f32_e32 v223, 0xbfb8aa3b, v65
	v_mul_f32_e32 v224, 0xbfb8aa3b, v66
	v_mul_f32_e32 v225, 0xbfb8aa3b, v67
	v_exp_f32_e32 v218, v218
	v_exp_f32_e32 v219, v219
	v_exp_f32_e32 v220, v220
	v_exp_f32_e32 v221, v221
	v_exp_f32_e32 v222, v222
	v_exp_f32_e32 v223, v223
	v_exp_f32_e32 v224, v224
	v_exp_f32_e32 v225, v225
	v_add_f32_e32 v218, 1.0, v218
	v_add_f32_e32 v219, 1.0, v219
	v_add_f32_e32 v220, 1.0, v220
	v_add_f32_e32 v221, 1.0, v221
	v_add_f32_e32 v222, 1.0, v222
	v_add_f32_e32 v223, 1.0, v223
	v_add_f32_e32 v224, 1.0, v224
	v_add_f32_e32 v225, 1.0, v225
	v_rcp_f32_e32 v218, v218
	v_rcp_f32_e32 v219, v219
	v_rcp_f32_e32 v220, v220
	v_rcp_f32_e32 v221, v221
	v_rcp_f32_e32 v222, v222
	v_rcp_f32_e32 v223, v223
	v_rcp_f32_e32 v224, v224
	v_rcp_f32_e32 v225, v225
	v_mul_f32_e32 v218, v72, v218
	v_mul_f32_e32 v219, v73, v219
	v_mul_f32_e32 v220, v74, v220
	v_mul_f32_e32 v221, v75, v221
	v_mul_f32_e32 v222, v64, v222
	v_mul_f32_e32 v223, v65, v223
	v_mul_f32_e32 v224, v66, v224
	v_mul_f32_e32 v225, v67, v225
	v_mul_f32_e32 v76, v76, v174
	v_mul_f32_e32 v77, v77, v174
	v_mul_f32_e32 v78, v78, v174
	v_mul_f32_e32 v79, v79, v174
	v_mul_f32_e32 v68, v68, v174
	v_mul_f32_e32 v69, v69, v174
	v_mul_f32_e32 v70, v70, v174
	v_mul_f32_e32 v71, v71, v174
	v_mul_f32_e32 v76, v76, v218
	v_mul_f32_e32 v77, v77, v219
	v_mul_f32_e32 v78, v78, v220
	v_mul_f32_e32 v79, v79, v221
	v_mul_f32_e32 v68, v68, v222
	v_mul_f32_e32 v69, v69, v223
	v_mul_f32_e32 v70, v70, v224
	v_mul_f32_e32 v71, v71, v225
	v_cvt_pk_bf16_f32 v230, v76, v77
	v_cvt_pk_bf16_f32 v231, v78, v79
	v_cvt_pk_bf16_f32 v232, v68, v69
	v_cvt_pk_bf16_f32 v233, v70, v71
	global_store_dwordx4 v[240:241], v[230:233], off
	v_mul_f32_e32 v56, v56, v178
	v_mul_f32_e32 v57, v57, v178
	v_mul_f32_e32 v58, v58, v178
	v_mul_f32_e32 v59, v59, v178
	v_mul_f32_e32 v48, v48, v178
	v_mul_f32_e32 v49, v49, v178
	v_mul_f32_e32 v50, v50, v178
	v_mul_f32_e32 v51, v51, v178
	v_mul_f32_e32 v218, 0xbfb8aa3b, v56
	v_mul_f32_e32 v219, 0xbfb8aa3b, v57
	v_mul_f32_e32 v220, 0xbfb8aa3b, v58
	v_mul_f32_e32 v221, 0xbfb8aa3b, v59
	v_mul_f32_e32 v222, 0xbfb8aa3b, v48
	v_mul_f32_e32 v223, 0xbfb8aa3b, v49
	v_mul_f32_e32 v224, 0xbfb8aa3b, v50
	v_mul_f32_e32 v225, 0xbfb8aa3b, v51
	v_exp_f32_e32 v218, v218
	v_exp_f32_e32 v219, v219
	v_exp_f32_e32 v220, v220
	v_exp_f32_e32 v221, v221
	v_exp_f32_e32 v222, v222
	v_exp_f32_e32 v223, v223
	v_exp_f32_e32 v224, v224
	v_exp_f32_e32 v225, v225
	v_add_f32_e32 v218, 1.0, v218
	v_add_f32_e32 v219, 1.0, v219
	v_add_f32_e32 v220, 1.0, v220
	v_add_f32_e32 v221, 1.0, v221
	v_add_f32_e32 v222, 1.0, v222
	v_add_f32_e32 v223, 1.0, v223
	v_add_f32_e32 v224, 1.0, v224
	v_add_f32_e32 v225, 1.0, v225
	v_rcp_f32_e32 v218, v218
	v_rcp_f32_e32 v219, v219
	v_rcp_f32_e32 v220, v220
	v_rcp_f32_e32 v221, v221
	v_rcp_f32_e32 v222, v222
	v_rcp_f32_e32 v223, v223
	v_rcp_f32_e32 v224, v224
	v_rcp_f32_e32 v225, v225
	v_mul_f32_e32 v218, v56, v218
	v_mul_f32_e32 v219, v57, v219
	v_mul_f32_e32 v220, v58, v220
	v_mul_f32_e32 v221, v59, v221
	v_mul_f32_e32 v222, v48, v222
	v_mul_f32_e32 v223, v49, v223
	v_mul_f32_e32 v224, v50, v224
	v_mul_f32_e32 v225, v51, v225
	v_mul_f32_e32 v60, v60, v178
	v_mul_f32_e32 v61, v61, v178
	v_mul_f32_e32 v62, v62, v178
	v_mul_f32_e32 v63, v63, v178
	v_mul_f32_e32 v52, v52, v178
	v_mul_f32_e32 v53, v53, v178
	v_mul_f32_e32 v54, v54, v178
	v_mul_f32_e32 v55, v55, v178
	v_mul_f32_e32 v60, v60, v218
	v_mul_f32_e32 v61, v61, v219
	v_mul_f32_e32 v62, v62, v220
	v_mul_f32_e32 v63, v63, v221
	v_mul_f32_e32 v52, v52, v222
	v_mul_f32_e32 v53, v53, v223
	v_mul_f32_e32 v54, v54, v224
	v_mul_f32_e32 v55, v55, v225
	v_cvt_pk_bf16_f32 v226, v60, v61
	v_cvt_pk_bf16_f32 v227, v62, v63
	v_cvt_pk_bf16_f32 v228, v52, v53
	v_cvt_pk_bf16_f32 v229, v54, v55
	v_lshl_add_u64 v[242:243], s[4:5], 3, v[234:235]
	global_store_dwordx4 v[242:243], v[226:229], off
	v_mul_f32_e32 v40, v40, v182
	v_mul_f32_e32 v41, v41, v182
; __device__ __forceinline__ unsigned cvt_pk_bf16(float lo, float hi) { unsigned r; asm volatile("v_cvt_pk_bf16_f32 %0, %1, %2" : "=v"(r) : "v"(lo), "v"(hi)); return r; }
; #define PG8_BAR __builtin_amdgcn_s_barrier()
;     __device__ __forceinline__ void operator()(const f32x4 (&acc)[2][2][4][2], const Unit& u, int wr, int wc, int fr, int fq) const {
;     ...
;                     for (int e = 0; e < 4; ++e) { const float gt = acc[ai][0][m][n][e] * rs, up = acc[ai][1][m][n][e] * rs;
;                         hv[n * 4 + e] = gt * __builtin_amdgcn_rcpf(1.f + __builtin_amdgcn_exp2f(-1.4426950408889634f * gt)) * up; }
;                 u32x4 w; w.x = cvt_pk_bf16(hv[0], hv[1]); w.y = cvt_pk_bf16(hv[2], hv[3]); w.z = cvt_pk_bf16(hv[4], hv[5]); w.w = cvt_pk_bf16(hv[6], hv[7]);
;                 *(u32x4*)(H + (size_t)row * 2816 + col0) = w;
; template <class Epi, class Sched, bool ALIGN_EPI = false, bool SP2 = false>
; __device__ __forceinline__ void gemm_phase(PG8_LAS unsigned char* lds, const Gemm g, const Sched& S, const Epi& E) {
;     ...
;         if constexpr (ALIGN_EPI) { if (wr == 0) PG8_BAR; }
;         if constexpr (!Epi::AFTER_DRAIN) { E(acc, cur, wr, wc, fr, fq); S.done(cur); }
;         if (!has_next) break;
	v_mul_f32_e32 v42, v42, v182
	v_mul_f32_e32 v43, v43, v182
	v_mul_f32_e32 v32, v32, v182
	v_mul_f32_e32 v33, v33, v182
	v_mul_f32_e32 v34, v34, v182
	v_mul_f32_e32 v35, v35, v182
	v_mul_f32_e32 v218, 0xbfb8aa3b, v40
	v_mul_f32_e32 v219, 0xbfb8aa3b, v41
	v_mul_f32_e32 v220, 0xbfb8aa3b, v42
	v_mul_f32_e32 v221, 0xbfb8aa3b, v43
	v_mul_f32_e32 v222, 0xbfb8aa3b, v32
	v_mul_f32_e32 v223, 0xbfb8aa3b, v33
	v_mul_f32_e32 v224, 0xbfb8aa3b, v34
	v_mul_f32_e32 v225, 0xbfb8aa3b, v35
	v_exp_f32_e32 v218, v218
	v_exp_f32_e32 v219, v219
	v_exp_f32_e32 v220, v220
	v_exp_f32_e32 v221, v221
	v_exp_f32_e32 v222, v222
	v_exp_f32_e32 v223, v223
	v_exp_f32_e32 v224, v224
	v_exp_f32_e32 v225, v225
	v_add_f32_e32 v218, 1.0, v218
	v_add_f32_e32 v219, 1.0, v219
	v_add_f32_e32 v220, 1.0, v220
	v_add_f32_e32 v221, 1.0, v221
	v_add_f32_e32 v222, 1.0, v222
	v_add_f32_e32 v223, 1.0, v223
	v_add_f32_e32 v224, 1.0, v224
	v_add_f32_e32 v225, 1.0, v225
	v_rcp_f32_e32 v218, v218
	v_rcp_f32_e32 v219, v219
	v_rcp_f32_e32 v220, v220
	v_rcp_f32_e32 v221, v221
	v_rcp_f32_e32 v222, v222
	v_rcp_f32_e32 v223, v223
	v_rcp_f32_e32 v224, v224
	v_rcp_f32_e32 v225, v225
	v_mul_f32_e32 v218, v40, v218
	v_mul_f32_e32 v219, v41, v219
	v_mul_f32_e32 v220, v42, v220
	v_mul_f32_e32 v221, v43, v221
	v_mul_f32_e32 v222, v32, v222
	v_mul_f32_e32 v223, v33, v223
	v_mul_f32_e32 v224, v34, v224
	v_mul_f32_e32 v225, v35, v225
	v_mul_f32_e32 v44, v44, v182
	v_mul_f32_e32 v45, v45, v182
	v_mul_f32_e32 v46, v46, v182
	v_mul_f32_e32 v47, v47, v182
	v_mul_f32_e32 v36, v36, v182
	v_mul_f32_e32 v37, v37, v182
	v_mul_f32_e32 v38, v38, v182
	v_mul_f32_e32 v39, v39, v182
	v_mul_f32_e32 v44, v44, v218
	v_mul_f32_e32 v45, v45, v219
	v_mul_f32_e32 v46, v46, v220
	v_mul_f32_e32 v47, v47, v221
	v_mul_f32_e32 v36, v36, v222
	v_mul_f32_e32 v37, v37, v223
	v_mul_f32_e32 v38, v38, v224
	v_mul_f32_e32 v39, v39, v225
	v_cvt_pk_bf16_f32 v230, v44, v45
	v_cvt_pk_bf16_f32 v231, v46, v47
	v_cvt_pk_bf16_f32 v232, v36, v37
	v_cvt_pk_bf16_f32 v233, v38, v39
	v_lshl_add_u64 v[242:243], s[4:5], 3, v[236:237]
	global_store_dwordx4 v[242:243], v[230:233], off
	v_mul_f32_e32 v24, v24, v186
	v_mul_f32_e32 v25, v25, v186
	v_mul_f32_e32 v26, v26, v186
	v_mul_f32_e32 v27, v27, v186
	v_mul_f32_e32 v16, v16, v186
	v_mul_f32_e32 v17, v17, v186
	v_mul_f32_e32 v18, v18, v186
	v_mul_f32_e32 v19, v19, v186
	v_mul_f32_e32 v218, 0xbfb8aa3b, v24
	v_mul_f32_e32 v219, 0xbfb8aa3b, v25
	v_mul_f32_e32 v220, 0xbfb8aa3b, v26
	v_mul_f32_e32 v221, 0xbfb8aa3b, v27
	v_mul_f32_e32 v222, 0xbfb8aa3b, v16
	v_mul_f32_e32 v223, 0xbfb8aa3b, v17
	v_mul_f32_e32 v224, 0xbfb8aa3b, v18
	v_mul_f32_e32 v225, 0xbfb8aa3b, v19
	v_exp_f32_e32 v218, v218
	v_exp_f32_e32 v219, v219
	v_exp_f32_e32 v220, v220
	v_exp_f32_e32 v221, v221
	v_exp_f32_e32 v222, v222
	v_exp_f32_e32 v223, v223
	v_exp_f32_e32 v224, v224
	v_exp_f32_e32 v225, v225
	v_add_f32_e32 v218, 1.0, v218
	v_add_f32_e32 v219, 1.0, v219
	v_add_f32_e32 v220, 1.0, v220
	v_add_f32_e32 v221, 1.0, v221
	v_add_f32_e32 v222, 1.0, v222
	v_add_f32_e32 v223, 1.0, v223
	v_add_f32_e32 v224, 1.0, v224
	v_add_f32_e32 v225, 1.0, v225
	v_rcp_f32_e32 v218, v218
	v_rcp_f32_e32 v219, v219
	v_rcp_f32_e32 v220, v220
	v_rcp_f32_e32 v221, v221
	v_rcp_f32_e32 v222, v222
	v_rcp_f32_e32 v223, v223
	v_rcp_f32_e32 v224, v224
	v_rcp_f32_e32 v225, v225
	v_mul_f32_e32 v218, v24, v218
	v_mul_f32_e32 v219, v25, v219
	v_mul_f32_e32 v220, v26, v220
	v_mul_f32_e32 v221, v27, v221
	v_mul_f32_e32 v222, v16, v222
	v_mul_f32_e32 v223, v17, v223
	v_mul_f32_e32 v224, v18, v224
	v_mul_f32_e32 v225, v19, v225
	v_mul_f32_e32 v28, v28, v186
	v_mul_f32_e32 v29, v29, v186
	v_mul_f32_e32 v30, v30, v186
	v_mul_f32_e32 v31, v31, v186
	v_mul_f32_e32 v20, v20, v186
	v_mul_f32_e32 v21, v21, v186
	v_mul_f32_e32 v22, v22, v186
	v_mul_f32_e32 v23, v23, v186
	v_mul_f32_e32 v28, v28, v218
	v_mul_f32_e32 v29, v29, v219
	v_mul_f32_e32 v30, v30, v220
	v_mul_f32_e32 v31, v31, v221
	v_mul_f32_e32 v20, v20, v222
	v_mul_f32_e32 v21, v21, v223
	v_mul_f32_e32 v22, v22, v224
	v_mul_f32_e32 v23, v23, v225
	v_cvt_pk_bf16_f32 v226, v28, v29
	v_cvt_pk_bf16_f32 v227, v30, v31
	v_cvt_pk_bf16_f32 v228, v20, v21
	v_cvt_pk_bf16_f32 v229, v22, v23
	v_lshl_add_u64 v[242:243], s[4:5], 3, v[238:239]
	global_store_dwordx4 v[242:243], v[226:229], off
	v_mul_f32_e32 v8, v8, v190
	v_mul_f32_e32 v9, v9, v190
	v_mul_f32_e32 v10, v10, v190
	v_mul_f32_e32 v11, v11, v190
	v_mul_f32_e32 v4, v4, v190
	v_mul_f32_e32 v5, v5, v190
	v_mul_f32_e32 v6, v6, v190
	v_mul_f32_e32 v7, v7, v190
	v_mul_f32_e32 v218, 0xbfb8aa3b, v8
	v_mul_f32_e32 v219, 0xbfb8aa3b, v9
	v_mul_f32_e32 v220, 0xbfb8aa3b, v10
	v_mul_f32_e32 v221, 0xbfb8aa3b, v11
	v_mul_f32_e32 v222, 0xbfb8aa3b, v4
	v_mul_f32_e32 v223, 0xbfb8aa3b, v5
	v_mul_f32_e32 v224, 0xbfb8aa3b, v6
	v_mul_f32_e32 v225, 0xbfb8aa3b, v7
	v_exp_f32_e32 v218, v218
	v_exp_f32_e32 v219, v219
	v_exp_f32_e32 v220, v220
	v_exp_f32_e32 v221, v221
	v_exp_f32_e32 v222, v222
	v_exp_f32_e32 v223, v223
	v_exp_f32_e32 v224, v224
	v_exp_f32_e32 v225, v225
	v_add_f32_e32 v218, 1.0, v218
	v_add_f32_e32 v219, 1.0, v219
	v_add_f32_e32 v220, 1.0, v220
	v_add_f32_e32 v221, 1.0, v221
	v_add_f32_e32 v222, 1.0, v222
	v_add_f32_e32 v223, 1.0, v223
	v_add_f32_e32 v224, 1.0, v224
	v_add_f32_e32 v225, 1.0, v225
	v_rcp_f32_e32 v218, v218
	v_rcp_f32_e32 v219, v219
	v_rcp_f32_e32 v220, v220
	v_rcp_f32_e32 v221, v221
	v_rcp_f32_e32 v222, v222
	v_rcp_f32_e32 v223, v223
	v_rcp_f32_e32 v224, v224
	v_rcp_f32_e32 v225, v225
	v_mul_f32_e32 v218, v8, v218
	v_mul_f32_e32 v219, v9, v219
	v_mul_f32_e32 v220, v10, v220
	v_mul_f32_e32 v221, v11, v221
	v_mul_f32_e32 v222, v4, v222
	v_mul_f32_e32 v223, v5, v223
	v_mul_f32_e32 v224, v6, v224
	v_mul_f32_e32 v225, v7, v225
	v_mul_f32_e32 v12, v12, v190
	v_mul_f32_e32 v13, v13, v190
	v_mul_f32_e32 v14, v14, v190
	v_mul_f32_e32 v15, v15, v190
	v_mul_f32_e32 v0, v0, v190
	v_mul_f32_e32 v1, v1, v190
	v_mul_f32_e32 v2, v2, v190
	v_mul_f32_e32 v3, v3, v190
	v_mul_f32_e32 v12, v12, v218
	v_mul_f32_e32 v13, v13, v219
	v_mul_f32_e32 v14, v14, v220
	v_mul_f32_e32 v15, v15, v221
	v_mul_f32_e32 v0, v0, v222
	v_mul_f32_e32 v1, v1, v223
	v_mul_f32_e32 v2, v2, v224
	v_mul_f32_e32 v3, v3, v225
	v_cvt_pk_bf16_f32 v230, v12, v13
	v_cvt_pk_bf16_f32 v231, v14, v15
	v_cvt_pk_bf16_f32 v232, v0, v1
	v_cvt_pk_bf16_f32 v233, v2, v3
	v_lshl_add_u64 v[242:243], s[4:5], 3, v[240:241]
	global_store_dwordx4 v[242:243], v[230:233], off
	s_and_b64 vcc, exec, s[38:39]
	s_mov_b64 s[4:5], -1
	s_cbranch_vccnz .LBB0_1159
	s_andn2_b64 vcc, exec, s[44:45]
	s_cbranch_vccnz .LBB0_1158
	s_barrier
	s_branch .LBB0_1158
